# attention loops modes 0/2: dead induction-pointer updates removed after SADDR conversion (2 VALU per 8 steps)
# baseline (speedup 1.0000x reference)
.LBB0_643:
	s_add_i32 s26, s25, 1
	s_cmp_lg_u32 s25, 4
	s_cselect_b32 s25, s26, 0
	s_waitcnt lgkmcnt(2)
	v_mfma_f32_32x32x16_bf16 v[82:97], v[240:243], v[158:161], v[34:49]
	v_exp_f32_e32 v102, v122
	v_exp_f32_e32 v103, v123
	v_exp_f32_e32 v104, v124
	v_exp_f32_e32 v105, v125
	v_exp_f32_e32 v98, v126
	v_exp_f32_e32 v99, v127
	v_exp_f32_e32 v100, v128
	v_exp_f32_e32 v101, v129
	s_waitcnt lgkmcnt(1)
	v_mfma_f32_32x32x16_bf16 v[66:81], v[244:247], v[158:161], v[34:49]
	v_exp_f32_e32 v194, v130
	v_exp_f32_e32 v187, v131
	v_exp_f32_e32 v186, v132
	v_exp_f32_e32 v185, v133
	v_exp_f32_e32 v133, v134
	v_exp_f32_e32 v132, v135
	v_exp_f32_e32 v131, v136
	v_exp_f32_e32 v130, v137
	v_mfma_f32_32x32x16_bf16 v[82:97], v[146:149], v[154:157], v[82:97]
	v_exp_f32_e32 v129, v106
	v_exp_f32_e32 v128, v107
	v_exp_f32_e32 v127, v108
	v_exp_f32_e32 v126, v109
	v_exp_f32_e32 v125, v110
	v_exp_f32_e32 v124, v111
	v_exp_f32_e32 v123, v112
	v_exp_f32_e32 v122, v113
	s_waitcnt lgkmcnt(0)
	v_mfma_f32_32x32x16_bf16 v[66:81], v[60:63], v[154:157], v[66:81]
	v_exp_f32_e32 v109, v114
	v_exp_f32_e32 v108, v115
	v_exp_f32_e32 v107, v116
	v_exp_f32_e32 v106, v117
	v_exp_f32_e32 v113, v118
	v_exp_f32_e32 v112, v119
	v_exp_f32_e32 v111, v120
	v_exp_f32_e32 v110, v121
	s_cmp_gt_i32 s25, 2
	s_cselect_b32 s26, -3, 2
	s_add_i32 s26, s26, s25
	s_mulk_i32 s26, 0x2400
	v_add_u32_e32 v1, s26, v182
	s_add_i32 s26, s25, 1
	s_cmp_lg_u32 s25, 4
	s_cselect_b32 s25, s26, 0
	s_add_i32 s26, s23, 8
	s_add_i32 s23, s23, 4
	s_cmp_ge_u32 s23, s2
	s_waitcnt vmcnt(3)
	ds_write_b128 v182, v[56:59] offset:27648
	s_waitcnt vmcnt(2)
	ds_write_b128 v1, v[52:55] offset:36864
	s_cbranch_scc1 .LBB0_666
	s_mov_b32 s23, s26
	s_branch .LBB0_641

.LBB0_663:
	s_add_i32 s28, s27, 1
	s_cmp_lg_u32 s27, 4
	s_cselect_b32 s27, s28, 0
	s_waitcnt lgkmcnt(6)
	v_mfma_f32_32x32x16_bf16 v[96:111], v[240:243], v[180:183], v[48:63]
	v_exp_f32_e32 v116, v136
	v_exp_f32_e32 v117, v137
	v_exp_f32_e32 v118, v138
	v_exp_f32_e32 v119, v139
	s_waitcnt lgkmcnt(5)
	v_mfma_f32_32x32x16_bf16 v[80:95], v[244:247], v[180:183], v[48:63]
	v_exp_f32_e32 v112, v140
	v_exp_f32_e32 v113, v141
	v_exp_f32_e32 v114, v142
	v_exp_f32_e32 v115, v143
	v_mfma_f32_32x32x16_bf16 v[96:111], v[164:167], v[176:179], v[96:111]
	v_exp_f32_e32 v187, v144
	v_exp_f32_e32 v186, v145
	v_exp_f32_e32 v185, v146
	v_exp_f32_e32 v184, v147
	s_waitcnt lgkmcnt(4)
	v_mfma_f32_32x32x16_bf16 v[80:95], v[160:163], v[176:179], v[80:95]
	v_exp_f32_e32 v147, v148
	v_exp_f32_e32 v146, v149
	v_exp_f32_e32 v145, v150
	v_exp_f32_e32 v144, v151
	s_waitcnt lgkmcnt(3)
	v_mfma_f32_32x32x16_bf16 v[96:111], v[74:77], v[172:175], v[96:111]
	v_exp_f32_e32 v143, v120
	v_exp_f32_e32 v142, v121
	v_exp_f32_e32 v141, v122
	v_exp_f32_e32 v140, v123
	s_waitcnt lgkmcnt(1)
	v_mfma_f32_32x32x16_bf16 v[80:95], v[70:73], v[172:175], v[80:95]
	v_exp_f32_e32 v139, v124
	v_exp_f32_e32 v138, v125
	v_exp_f32_e32 v137, v126
	v_exp_f32_e32 v136, v127
	v_mfma_f32_32x32x16_bf16 v[96:111], v[66:69], v[168:171], v[96:111]
	v_exp_f32_e32 v123, v128
	v_exp_f32_e32 v122, v129
	v_exp_f32_e32 v121, v130
	v_exp_f32_e32 v120, v131
	s_waitcnt lgkmcnt(0)
	v_mfma_f32_32x32x16_bf16 v[80:95], v[10:13], v[168:171], v[80:95]
	v_exp_f32_e32 v127, v132
	v_exp_f32_e32 v126, v133
	v_exp_f32_e32 v125, v134
	v_exp_f32_e32 v124, v135
	s_cmp_gt_i32 s27, 2
	s_cselect_b32 s28, -3, 2
	s_add_i32 s28, s28, s27
	s_mulk_i32 s28, 0x2400
	v_add_u32_e32 v1, s28, v208
	s_add_i32 s28, s27, 1
	s_cmp_lg_u32 s27, 4
	s_cselect_b32 s27, s28, 0
	s_add_i32 s28, s13, 8
	s_add_i32 s13, s13, 4
	s_cmp_ge_u32 s13, s2
	s_waitcnt vmcnt(3)
	ds_write_b128 v208, v[6:9] offset:27648
	s_waitcnt vmcnt(2)
	ds_write_b128 v1, v[2:5] offset:36864
	s_cbranch_scc1 .LBB0_682
	s_mov_b32 s13, s28
	s_branch .LBB0_661
